# prologue: batch x-row loads, hoist 64 serialized scale loads into one vector load + readlane
# baseline (speedup 1.0000x reference)
.LBB0_54:
	s_waitcnt lgkmcnt(0)
	global_load_dwordx4 v[100:103], v[2:3], off offset:-4096
	global_load_dwordx4 v[104:107], v[2:3], off offset:-3072
	global_load_dwordx4 v[108:111], v[2:3], off offset:-2048
	global_load_dwordx4 v[112:115], v[2:3], off offset:-1024
	global_load_dwordx4 v[116:119], v[2:3], off
	global_load_dwordx4 v[120:123], v[2:3], off offset:1024
	global_load_dwordx4 v[124:127], v[2:3], off offset:2048
	global_load_dwordx4 v[128:131], v[2:3], off offset:3072
	v_lshl_add_u64 v[6:7], s[38:39], 0, v[4:5]
	v_add_co_u32_e64 v6, s[0:1], s8, v6
	s_nop 1
	v_addc_co_u32_e64 v7, s[0:1], 0, v7, s[0:1]
	s_waitcnt vmcnt(7)
	v_and_b32_sdwa v91, v100, v15 dst_sel:DWORD dst_unused:UNUSED_PAD src0_sel:WORD_1 src1_sel:DWORD
	v_and_b32_sdwa v92, v103, v15 dst_sel:DWORD dst_unused:UNUSED_PAD src0_sel:WORD_1 src1_sel:DWORD
	v_and_b32_sdwa v93, v101, v15 dst_sel:DWORD dst_unused:UNUSED_PAD src0_sel:WORD_1 src1_sel:DWORD
	v_and_b32_sdwa v90, v102, v15 dst_sel:DWORD dst_unused:UNUSED_PAD src0_sel:WORD_1 src1_sel:DWORD
	v_add3_u32 v94, v100, v91, s7
	v_add3_u32 v91, v103, v92, s7
	v_add3_u32 v92, v101, v93, s7
	v_add3_u32 v90, v102, v90, s7
	v_and_b32_e32 v91, 0xffff0000, v91
	v_and_b32_e32 v92, 0xffff0000, v92
	v_or_b32_sdwa v97, v91, v90 dst_sel:DWORD dst_unused:UNUSED_PAD src0_sel:DWORD src1_sel:WORD_1
	v_or_b32_sdwa v96, v92, v94 dst_sel:DWORD dst_unused:UNUSED_PAD src0_sel:DWORD src1_sel:WORD_1
	global_store_dwordx2 v[6:7], v[96:97], off
	v_mul_f32_e32 v132, v101, v101
	v_mul_f32_e32 v133, v103, v103
	v_fmac_f32_e32 v132, v100, v100
	v_fmac_f32_e32 v133, v102, v102
	v_add_f32_e32 v16, v132, v133
	s_waitcnt vmcnt(7)
	v_and_b32_sdwa v91, v104, v15 dst_sel:DWORD dst_unused:UNUSED_PAD src0_sel:WORD_1 src1_sel:DWORD
	v_and_b32_sdwa v92, v107, v15 dst_sel:DWORD dst_unused:UNUSED_PAD src0_sel:WORD_1 src1_sel:DWORD
	v_and_b32_sdwa v93, v105, v15 dst_sel:DWORD dst_unused:UNUSED_PAD src0_sel:WORD_1 src1_sel:DWORD
	v_and_b32_sdwa v90, v106, v15 dst_sel:DWORD dst_unused:UNUSED_PAD src0_sel:WORD_1 src1_sel:DWORD
	v_add3_u32 v94, v104, v91, s7
	v_add3_u32 v91, v107, v92, s7
	v_add3_u32 v92, v105, v93, s7
	v_add3_u32 v90, v106, v90, s7
	v_and_b32_e32 v91, 0xffff0000, v91
	v_and_b32_e32 v92, 0xffff0000, v92
	v_or_b32_sdwa v99, v91, v90 dst_sel:DWORD dst_unused:UNUSED_PAD src0_sel:DWORD src1_sel:WORD_1
	v_or_b32_sdwa v98, v92, v94 dst_sel:DWORD dst_unused:UNUSED_PAD src0_sel:DWORD src1_sel:WORD_1
	global_store_dwordx2 v[6:7], v[98:99], off offset:512
	v_mul_f32_e32 v132, v105, v105
	v_mul_f32_e32 v133, v107, v107
	v_fmac_f32_e32 v132, v104, v104
	v_fmac_f32_e32 v133, v106, v106
	v_add_f32_e32 v132, v132, v133
	v_add_f32_e32 v16, v16, v132
	s_waitcnt vmcnt(7)
	v_and_b32_sdwa v91, v108, v15 dst_sel:DWORD dst_unused:UNUSED_PAD src0_sel:WORD_1 src1_sel:DWORD
	v_and_b32_sdwa v92, v111, v15 dst_sel:DWORD dst_unused:UNUSED_PAD src0_sel:WORD_1 src1_sel:DWORD
	v_and_b32_sdwa v93, v109, v15 dst_sel:DWORD dst_unused:UNUSED_PAD src0_sel:WORD_1 src1_sel:DWORD
	v_and_b32_sdwa v90, v110, v15 dst_sel:DWORD dst_unused:UNUSED_PAD src0_sel:WORD_1 src1_sel:DWORD
	v_add3_u32 v94, v108, v91, s7
	v_add3_u32 v91, v111, v92, s7
	v_add3_u32 v92, v109, v93, s7
	v_add3_u32 v90, v110, v90, s7
	v_and_b32_e32 v91, 0xffff0000, v91
	v_and_b32_e32 v92, 0xffff0000, v92
	v_or_b32_sdwa v97, v91, v90 dst_sel:DWORD dst_unused:UNUSED_PAD src0_sel:DWORD src1_sel:WORD_1
	v_or_b32_sdwa v96, v92, v94 dst_sel:DWORD dst_unused:UNUSED_PAD src0_sel:DWORD src1_sel:WORD_1
	global_store_dwordx2 v[6:7], v[96:97], off offset:1024
	v_mul_f32_e32 v132, v109, v109
	v_mul_f32_e32 v133, v111, v111
	v_fmac_f32_e32 v132, v108, v108
	v_fmac_f32_e32 v133, v110, v110
	v_add_f32_e32 v132, v132, v133
	v_add_f32_e32 v16, v16, v132
	s_waitcnt vmcnt(7)
	v_and_b32_sdwa v91, v112, v15 dst_sel:DWORD dst_unused:UNUSED_PAD src0_sel:WORD_1 src1_sel:DWORD
	v_and_b32_sdwa v92, v115, v15 dst_sel:DWORD dst_unused:UNUSED_PAD src0_sel:WORD_1 src1_sel:DWORD
	v_and_b32_sdwa v93, v113, v15 dst_sel:DWORD dst_unused:UNUSED_PAD src0_sel:WORD_1 src1_sel:DWORD
	v_and_b32_sdwa v90, v114, v15 dst_sel:DWORD dst_unused:UNUSED_PAD src0_sel:WORD_1 src1_sel:DWORD
	v_add3_u32 v94, v112, v91, s7
	v_add3_u32 v91, v115, v92, s7
	v_add3_u32 v92, v113, v93, s7
	v_add3_u32 v90, v114, v90, s7
	v_and_b32_e32 v91, 0xffff0000, v91
	v_and_b32_e32 v92, 0xffff0000, v92
	v_or_b32_sdwa v99, v91, v90 dst_sel:DWORD dst_unused:UNUSED_PAD src0_sel:DWORD src1_sel:WORD_1
	v_or_b32_sdwa v98, v92, v94 dst_sel:DWORD dst_unused:UNUSED_PAD src0_sel:DWORD src1_sel:WORD_1
	global_store_dwordx2 v[6:7], v[98:99], off offset:1536
	v_mul_f32_e32 v132, v113, v113
	v_mul_f32_e32 v133, v115, v115
	v_fmac_f32_e32 v132, v112, v112
	v_fmac_f32_e32 v133, v114, v114
	v_add_f32_e32 v132, v132, v133
	v_add_f32_e32 v16, v16, v132
	s_waitcnt vmcnt(7)
	v_and_b32_sdwa v91, v116, v15 dst_sel:DWORD dst_unused:UNUSED_PAD src0_sel:WORD_1 src1_sel:DWORD
	v_and_b32_sdwa v92, v119, v15 dst_sel:DWORD dst_unused:UNUSED_PAD src0_sel:WORD_1 src1_sel:DWORD
	v_and_b32_sdwa v93, v117, v15 dst_sel:DWORD dst_unused:UNUSED_PAD src0_sel:WORD_1 src1_sel:DWORD
	v_and_b32_sdwa v90, v118, v15 dst_sel:DWORD dst_unused:UNUSED_PAD src0_sel:WORD_1 src1_sel:DWORD
	v_add3_u32 v94, v116, v91, s7
	v_add3_u32 v91, v119, v92, s7
	v_add3_u32 v92, v117, v93, s7
	v_add3_u32 v90, v118, v90, s7
	v_and_b32_e32 v91, 0xffff0000, v91
	v_and_b32_e32 v92, 0xffff0000, v92
	v_or_b32_sdwa v97, v91, v90 dst_sel:DWORD dst_unused:UNUSED_PAD src0_sel:DWORD src1_sel:WORD_1
	v_or_b32_sdwa v96, v92, v94 dst_sel:DWORD dst_unused:UNUSED_PAD src0_sel:DWORD src1_sel:WORD_1
	global_store_dwordx2 v[6:7], v[96:97], off offset:2048
	v_mul_f32_e32 v132, v117, v117
	v_mul_f32_e32 v133, v119, v119
	v_fmac_f32_e32 v132, v116, v116
	v_fmac_f32_e32 v133, v118, v118
	v_add_f32_e32 v132, v132, v133
	v_add_f32_e32 v16, v16, v132
	s_waitcnt vmcnt(7)
	v_and_b32_sdwa v91, v120, v15 dst_sel:DWORD dst_unused:UNUSED_PAD src0_sel:WORD_1 src1_sel:DWORD
	v_and_b32_sdwa v92, v123, v15 dst_sel:DWORD dst_unused:UNUSED_PAD src0_sel:WORD_1 src1_sel:DWORD
	v_and_b32_sdwa v93, v121, v15 dst_sel:DWORD dst_unused:UNUSED_PAD src0_sel:WORD_1 src1_sel:DWORD
	v_and_b32_sdwa v90, v122, v15 dst_sel:DWORD dst_unused:UNUSED_PAD src0_sel:WORD_1 src1_sel:DWORD
	v_add3_u32 v94, v120, v91, s7
	v_add3_u32 v91, v123, v92, s7
	v_add3_u32 v92, v121, v93, s7
	v_add3_u32 v90, v122, v90, s7
	v_and_b32_e32 v91, 0xffff0000, v91
	v_and_b32_e32 v92, 0xffff0000, v92
	v_or_b32_sdwa v99, v91, v90 dst_sel:DWORD dst_unused:UNUSED_PAD src0_sel:DWORD src1_sel:WORD_1
	v_or_b32_sdwa v98, v92, v94 dst_sel:DWORD dst_unused:UNUSED_PAD src0_sel:DWORD src1_sel:WORD_1
	global_store_dwordx2 v[6:7], v[98:99], off offset:2560
	v_mul_f32_e32 v132, v121, v121
	v_mul_f32_e32 v133, v123, v123
	v_fmac_f32_e32 v132, v120, v120
	v_fmac_f32_e32 v133, v122, v122
	v_add_f32_e32 v132, v132, v133
	v_add_f32_e32 v16, v16, v132
	s_waitcnt vmcnt(7)
	v_and_b32_sdwa v91, v124, v15 dst_sel:DWORD dst_unused:UNUSED_PAD src0_sel:WORD_1 src1_sel:DWORD
	v_and_b32_sdwa v92, v127, v15 dst_sel:DWORD dst_unused:UNUSED_PAD src0_sel:WORD_1 src1_sel:DWORD
	v_and_b32_sdwa v93, v125, v15 dst_sel:DWORD dst_unused:UNUSED_PAD src0_sel:WORD_1 src1_sel:DWORD
	v_and_b32_sdwa v90, v126, v15 dst_sel:DWORD dst_unused:UNUSED_PAD src0_sel:WORD_1 src1_sel:DWORD
	v_add3_u32 v94, v124, v91, s7
	v_add3_u32 v91, v127, v92, s7
	v_add3_u32 v92, v125, v93, s7
	v_add3_u32 v90, v126, v90, s7
	v_and_b32_e32 v91, 0xffff0000, v91
	v_and_b32_e32 v92, 0xffff0000, v92
	v_or_b32_sdwa v97, v91, v90 dst_sel:DWORD dst_unused:UNUSED_PAD src0_sel:DWORD src1_sel:WORD_1
	v_or_b32_sdwa v96, v92, v94 dst_sel:DWORD dst_unused:UNUSED_PAD src0_sel:DWORD src1_sel:WORD_1
	global_store_dwordx2 v[6:7], v[96:97], off offset:3072
	v_mul_f32_e32 v132, v125, v125
	v_mul_f32_e32 v133, v127, v127
	v_fmac_f32_e32 v132, v124, v124
	v_fmac_f32_e32 v133, v126, v126
	v_add_f32_e32 v132, v132, v133
	v_add_f32_e32 v16, v16, v132
	s_waitcnt vmcnt(7)
	v_and_b32_sdwa v91, v128, v15 dst_sel:DWORD dst_unused:UNUSED_PAD src0_sel:WORD_1 src1_sel:DWORD
	v_and_b32_sdwa v92, v131, v15 dst_sel:DWORD dst_unused:UNUSED_PAD src0_sel:WORD_1 src1_sel:DWORD
	v_and_b32_sdwa v93, v129, v15 dst_sel:DWORD dst_unused:UNUSED_PAD src0_sel:WORD_1 src1_sel:DWORD
	v_and_b32_sdwa v90, v130, v15 dst_sel:DWORD dst_unused:UNUSED_PAD src0_sel:WORD_1 src1_sel:DWORD
	v_add3_u32 v94, v128, v91, s7
	v_add3_u32 v91, v131, v92, s7
	v_add3_u32 v92, v129, v93, s7
	v_add3_u32 v90, v130, v90, s7
	v_and_b32_e32 v91, 0xffff0000, v91
	v_and_b32_e32 v92, 0xffff0000, v92
	v_or_b32_sdwa v99, v91, v90 dst_sel:DWORD dst_unused:UNUSED_PAD src0_sel:DWORD src1_sel:WORD_1
	v_or_b32_sdwa v98, v92, v94 dst_sel:DWORD dst_unused:UNUSED_PAD src0_sel:DWORD src1_sel:WORD_1
	global_store_dwordx2 v[6:7], v[98:99], off offset:3584
	v_mul_f32_e32 v132, v129, v129
	v_mul_f32_e32 v133, v131, v131
	v_fmac_f32_e32 v132, v128, v128
	v_fmac_f32_e32 v133, v130, v130
	v_add_f32_e32 v132, v132, v133
	v_add_f32_e32 v16, v16, v132
	ds_bpermute_b32 v17, v8, v16
	s_waitcnt lgkmcnt(0)
	v_add_f32_e32 v16, v16, v17
	ds_bpermute_b32 v17, v9, v16
	s_waitcnt lgkmcnt(0)
	v_add_f32_e32 v16, v16, v17
	ds_bpermute_b32 v17, v11, v16
	s_waitcnt lgkmcnt(0)
	v_add_f32_e32 v16, v16, v17
	ds_bpermute_b32 v17, v12, v16
	s_waitcnt lgkmcnt(0)
	v_add_f32_e32 v16, v16, v17
	ds_bpermute_b32 v17, v13, v16
	s_waitcnt lgkmcnt(0)
	v_add_f32_e32 v16, v16, v17
	ds_bpermute_b32 v17, v14, v16
	s_and_saveexec_b64 s[0:1], vcc
	s_cbranch_execz .LBB0_53
	s_add_u32 s10, s38, s4
	s_addc_u32 s11, s39, s5
	s_waitcnt lgkmcnt(0)
	v_add_f32_e32 v16, v16, v17
	v_mov_b64_e32 v[6:7], s[10:11]
	flat_store_dword v[6:7], v16
	s_branch .LBB0_53

.LBB0_79:
	s_or_b64 exec, exec, s[4:5]
	v_max_i32_e32 v2, 0, v2
	v_lshl_add_u64 v[6:7], v[2:3], 2, s[58:59]
	s_lshl_b32 s38, s13, 6
	v_mad_i64_i32 v[6:7], s[0:1], s38, v14, v[6:7]
	v_add_co_u32_e32 v8, vcc, 0xc000, v6
	v_cmp_lt_i32_e64 s[4:5], -1, v59
	s_nop 0
	v_addc_co_u32_e32 v9, vcc, 0, v7, vcc
	v_add_co_u32_e32 v16, vcc, 0x18000, v6
	s_ashr_i32 s39, s38, 31
	s_waitcnt lgkmcnt(0)
	v_addc_co_u32_e32 v17, vcc, 0, v7, vcc
	v_add_co_u32_e32 v18, vcc, 0x24000, v6
	v_cmp_ne_u32_e64 s[0:1], 1, v223
	s_nop 0
	v_addc_co_u32_e32 v19, vcc, 0, v7, vcc
	v_add_co_u32_e32 v20, vcc, 0x31000, v6
	s_nop 1
	v_addc_co_u32_e32 v21, vcc, 0, v7, vcc
	v_add_co_u32_e32 v22, vcc, 0x3d000, v6
	s_nop 1
	v_addc_co_u32_e32 v23, vcc, 0, v7, vcc
	v_add_co_u32_e32 v24, vcc, 0x49000, v6
	s_nop 1
	v_addc_co_u32_e32 v25, vcc, 0, v7, vcc
	v_add_co_u32_e32 v26, vcc, 0x55000, v6
	s_nop 1
	v_addc_co_u32_e32 v27, vcc, 0, v7, vcc
	global_load_dword v74, v[6:7], off
	global_load_dword v73, v[8:9], off offset:1088
	global_load_dword v72, v[16:17], off offset:2176
	global_load_dword v71, v[18:19], off offset:3264
	global_load_dword v70, v[20:21], off offset:256
	global_load_dword v68, v[22:23], off offset:1344
	global_load_dword v66, v[24:25], off offset:2432
	global_load_dword v64, v[26:27], off offset:3520
	v_add_co_u32_e32 v8, vcc, 0x62000, v6
	v_addc_co_u32_e32 v9, vcc, 0, v7, vcc
	v_add_co_u32_e32 v16, vcc, 0x6e000, v6
	s_nop 1
	v_addc_co_u32_e32 v17, vcc, 0, v7, vcc
	v_add_co_u32_e32 v18, vcc, 0x7a000, v6
	s_nop 1
	v_addc_co_u32_e32 v19, vcc, 0, v7, vcc
	v_add_co_u32_e32 v20, vcc, 0x86000, v6
	s_nop 1
	v_addc_co_u32_e32 v21, vcc, 0, v7, vcc
	v_add_co_u32_e32 v22, vcc, 0x93000, v6
	s_nop 1
	v_addc_co_u32_e32 v23, vcc, 0, v7, vcc
	v_add_co_u32_e32 v24, vcc, 0x9f000, v6
	s_nop 1
	v_addc_co_u32_e32 v25, vcc, 0, v7, vcc
	v_add_co_u32_e32 v26, vcc, 0xab000, v6
	s_nop 1
	v_addc_co_u32_e32 v27, vcc, 0, v7, vcc
	v_add_co_u32_e32 v28, vcc, 0xb7000, v6
	s_nop 1
	v_addc_co_u32_e32 v29, vcc, 0, v7, vcc
	global_load_dword v69, v[8:9], off offset:512
	global_load_dword v67, v[16:17], off offset:1600
	global_load_dword v65, v[18:19], off offset:2688
	global_load_dword v63, v[20:21], off offset:3776
	global_load_dword v62, v[22:23], off offset:768
	global_load_dword v60, v[24:25], off offset:1856
	global_load_dword v57, v[26:27], off offset:2944
	global_load_dword v55, v[28:29], off offset:4032
	v_add_co_u32_e32 v8, vcc, 0xc4000, v6
	s_nop 1
	v_addc_co_u32_e32 v9, vcc, 0, v7, vcc
	v_add_co_u32_e32 v16, vcc, 0xd0000, v6
	s_nop 1
	v_addc_co_u32_e32 v17, vcc, 0, v7, vcc
	v_add_co_u32_e32 v18, vcc, 0xdc000, v6
	s_nop 1
	v_addc_co_u32_e32 v19, vcc, 0, v7, vcc
	v_add_co_u32_e32 v20, vcc, 0xe9000, v6
	s_nop 1
	v_addc_co_u32_e32 v21, vcc, 0, v7, vcc
	v_add_co_u32_e32 v22, vcc, 0xf5000, v6
	s_nop 1
	v_addc_co_u32_e32 v23, vcc, 0, v7, vcc
	v_add_co_u32_e32 v24, vcc, 0x101000, v6
	s_nop 1
	v_addc_co_u32_e32 v25, vcc, 0, v7, vcc
	v_add_co_u32_e32 v26, vcc, 0x10d000, v6
	s_nop 1
	v_addc_co_u32_e32 v27, vcc, 0, v7, vcc
	v_add_co_u32_e32 v28, vcc, 0x11a000, v6
	s_nop 1
	v_addc_co_u32_e32 v29, vcc, 0, v7, vcc
	global_load_dword v61, v[8:9], off offset:1024
	global_load_dword v58, v[16:17], off offset:2112
	global_load_dword v56, v[18:19], off offset:3200
	global_load_dword v54, v[20:21], off offset:192
	global_load_dword v53, v[22:23], off offset:1280
	global_load_dword v51, v[24:25], off offset:2368
	global_load_dword v49, v[26:27], off offset:3456
	global_load_dword v47, v[28:29], off offset:448
	v_add_co_u32_e32 v8, vcc, 0x126000, v6
	s_nop 1
	v_addc_co_u32_e32 v9, vcc, 0, v7, vcc
	v_add_co_u32_e32 v16, vcc, 0x132000, v6
	s_nop 1
	v_addc_co_u32_e32 v17, vcc, 0, v7, vcc
	v_add_co_u32_e32 v18, vcc, 0x13e000, v6
	s_nop 1
	v_addc_co_u32_e32 v19, vcc, 0, v7, vcc
	v_add_co_u32_e32 v20, vcc, 0x14b000, v6
	s_nop 1
	v_addc_co_u32_e32 v21, vcc, 0, v7, vcc
	v_add_co_u32_e32 v22, vcc, 0x157000, v6
	s_nop 1
	v_addc_co_u32_e32 v23, vcc, 0, v7, vcc
	v_add_co_u32_e32 v24, vcc, 0x163000, v6
	s_nop 1
	v_addc_co_u32_e32 v25, vcc, 0, v7, vcc
	v_add_co_u32_e32 v26, vcc, 0x16f000, v6
	s_nop 1
	v_addc_co_u32_e32 v27, vcc, 0, v7, vcc
	v_add_co_u32_e32 v28, vcc, 0x17c000, v6
	s_nop 1
	v_addc_co_u32_e32 v29, vcc, 0, v7, vcc
	global_load_dword v52, v[8:9], off offset:1536
	global_load_dword v50, v[16:17], off offset:2624
	global_load_dword v48, v[18:19], off offset:3712
	global_load_dword v46, v[20:21], off offset:704
	global_load_dword v45, v[22:23], off offset:1792
	global_load_dword v43, v[24:25], off offset:2880
	global_load_dword v41, v[26:27], off offset:3968
	global_load_dword v39, v[28:29], off offset:960
	v_add_co_u32_e32 v8, vcc, 0x188000, v6
	s_nop 1
	v_addc_co_u32_e32 v9, vcc, 0, v7, vcc
	v_add_co_u32_e32 v16, vcc, 0x194000, v6
	s_nop 1
	v_addc_co_u32_e32 v17, vcc, 0, v7, vcc
	v_add_co_u32_e32 v18, vcc, 0x1a1000, v6
	s_nop 1
	v_addc_co_u32_e32 v19, vcc, 0, v7, vcc
	v_add_co_u32_e32 v20, vcc, 0x1ad000, v6
	s_nop 1
	v_addc_co_u32_e32 v21, vcc, 0, v7, vcc
	v_add_co_u32_e32 v22, vcc, 0x1b9000, v6
	s_nop 1
	v_addc_co_u32_e32 v23, vcc, 0, v7, vcc
	v_add_co_u32_e32 v24, vcc, 0x1c5000, v6
	s_nop 1
	v_addc_co_u32_e32 v25, vcc, 0, v7, vcc
	v_add_co_u32_e32 v26, vcc, 0x1d2000, v6
	s_nop 1
	v_addc_co_u32_e32 v27, vcc, 0, v7, vcc
	v_add_co_u32_e32 v28, vcc, 0x1de000, v6
	s_nop 1
	v_addc_co_u32_e32 v29, vcc, 0, v7, vcc
	global_load_dword v44, v[8:9], off offset:2048
	global_load_dword v42, v[16:17], off offset:3136
	global_load_dword v40, v[18:19], off offset:128
	global_load_dword v38, v[20:21], off offset:1216
	global_load_dword v37, v[22:23], off offset:2304
	global_load_dword v35, v[24:25], off offset:3392
	global_load_dword v33, v[26:27], off offset:384
	global_load_dword v31, v[28:29], off offset:1472
	v_add_co_u32_e32 v8, vcc, 0x1ea000, v6
	s_nop 1
	v_addc_co_u32_e32 v9, vcc, 0, v7, vcc
	v_add_co_u32_e32 v16, vcc, 0x1f6000, v6
	s_nop 1
	v_addc_co_u32_e32 v17, vcc, 0, v7, vcc
	v_add_co_u32_e32 v18, vcc, 0x203000, v6
	s_nop 1
	v_addc_co_u32_e32 v19, vcc, 0, v7, vcc
	v_add_co_u32_e32 v20, vcc, 0x20f000, v6
	s_nop 1
	v_addc_co_u32_e32 v21, vcc, 0, v7, vcc
	v_add_co_u32_e32 v22, vcc, 0x21b000, v6
	s_nop 1
	v_addc_co_u32_e32 v23, vcc, 0, v7, vcc
	v_add_co_u32_e32 v24, vcc, 0x227000, v6
	s_nop 1
	v_addc_co_u32_e32 v25, vcc, 0, v7, vcc
	v_add_co_u32_e32 v76, vcc, 0x234000, v6
	s_nop 1
	v_addc_co_u32_e32 v77, vcc, 0, v7, vcc
	v_add_co_u32_e32 v78, vcc, 0x240000, v6
	s_nop 1
	v_addc_co_u32_e32 v79, vcc, 0, v7, vcc
	global_load_dword v36, v[8:9], off offset:2560
	global_load_dword v34, v[16:17], off offset:3648
	global_load_dword v32, v[18:19], off offset:640
	global_load_dword v30, v[20:21], off offset:1728
	global_load_dword v29, v[22:23], off offset:2816
	global_load_dword v27, v[24:25], off offset:3904
	s_nop 0
	global_load_dword v25, v[76:77], off offset:896
	global_load_dword v23, v[78:79], off offset:1984
	v_add_co_u32_e32 v8, vcc, 0x24c000, v6
	s_nop 1
	v_addc_co_u32_e32 v9, vcc, 0, v7, vcc
	v_add_co_u32_e32 v16, vcc, 0x259000, v6
	s_nop 1
	v_addc_co_u32_e32 v17, vcc, 0, v7, vcc
	v_add_co_u32_e32 v18, vcc, 0x265000, v6
	s_nop 1
	v_addc_co_u32_e32 v19, vcc, 0, v7, vcc
	v_add_co_u32_e32 v20, vcc, 0x271000, v6
	s_nop 1
	v_addc_co_u32_e32 v21, vcc, 0, v7, vcc
	v_add_co_u32_e32 v76, vcc, 0x27d000, v6
	s_nop 1
	v_addc_co_u32_e32 v77, vcc, 0, v7, vcc
	v_add_co_u32_e32 v78, vcc, 0x28a000, v6
	s_nop 1
	v_addc_co_u32_e32 v79, vcc, 0, v7, vcc
	v_add_co_u32_e32 v80, vcc, 0x296000, v6
	s_nop 1
	v_addc_co_u32_e32 v81, vcc, 0, v7, vcc
	v_add_co_u32_e32 v82, vcc, 0x2a2000, v6
	s_nop 1
	v_addc_co_u32_e32 v83, vcc, 0, v7, vcc
	global_load_dword v28, v[8:9], off offset:3072
	global_load_dword v26, v[16:17], off offset:64
	global_load_dword v24, v[18:19], off offset:1152
	global_load_dword v22, v[20:21], off offset:2240
	s_nop 0
	global_load_dword v21, v[76:77], off offset:3328
	global_load_dword v19, v[78:79], off offset:320
	global_load_dword v17, v[80:81], off offset:1408
	global_load_dword v15, v[82:83], off offset:2496
	v_add_co_u32_e32 v8, vcc, 0x2ae000, v6
	s_nop 1
	v_addc_co_u32_e32 v9, vcc, 0, v7, vcc
	v_add_co_u32_e32 v76, vcc, 0x2bb000, v6
	s_nop 1
	v_addc_co_u32_e32 v77, vcc, 0, v7, vcc
	v_add_co_u32_e32 v78, vcc, 0x2c7000, v6
	s_nop 1
	v_addc_co_u32_e32 v79, vcc, 0, v7, vcc
	v_add_co_u32_e32 v80, vcc, 0x2d3000, v6
	s_nop 1
	v_addc_co_u32_e32 v81, vcc, 0, v7, vcc
	v_add_co_u32_e32 v82, vcc, 0x2df000, v6
	s_nop 1
	v_addc_co_u32_e32 v83, vcc, 0, v7, vcc
	v_add_co_u32_e32 v84, vcc, 0x2ec000, v6
	s_nop 1
	v_addc_co_u32_e32 v85, vcc, 0, v7, vcc
	v_add_co_u32_e32 v86, vcc, 0x2f8000, v6
	s_nop 1
	v_addc_co_u32_e32 v87, vcc, 0, v7, vcc
	v_add_co_u32_e32 v88, vcc, 0x304000, v6
	s_nop 1
	v_addc_co_u32_e32 v89, vcc, 0, v7, vcc
	global_load_dword v20, v[8:9], off offset:3584
	global_load_dword v18, v[76:77], off offset:576
	global_load_dword v16, v[78:79], off offset:1664
	s_nop 0
	global_load_dword v9, v[80:81], off offset:2752
	global_load_dword v7, v[82:83], off offset:3840
	global_load_dword v6, v[84:85], off offset:832
	global_load_dword v2, v[86:87], off offset:1920
	global_load_dword v8, v[88:89], off offset:3008
	s_andn2_b64 vcc, exec, s[36:37]
	s_cbranch_vccnz .Lwja_noscale
	s_lshl_b64 s[14:15], s[38:39], 2
	s_add_u32 s14, s56, s14
	s_addc_u32 s15, s57, s15
	v_lshlrev_b32_e32 v101, 2, v1
	global_load_dword v100, v101, s[14:15]
.Lwja_noscale:
	s_waitcnt vmcnt(0)
	v_cndmask_b32_e64 v59, 0, v74, s[4:5]
	s_andn2_b64 vcc, exec, s[36:37]
	s_cbranch_vccnz .LBB0_81
	v_readlane_b32 s14, v100, 0
	s_nop 1
	v_mul_f32_e32 v59, s14, v59
.LBB0_81:
	ds_write_b32 v11, v59
	s_and_b64 vcc, exec, s[0:1]
	v_cndmask_b32_e64 v59, 0, v73, s[4:5]
	s_cbranch_vccnz .LBB0_83
	v_readlane_b32 s14, v100, 1
	s_nop 1
	v_mul_f32_e32 v59, s14, v59
.LBB0_83:
	ds_write_b32 v11, v59 offset:260
	s_and_b64 vcc, exec, s[0:1]
	v_cndmask_b32_e64 v59, 0, v72, s[4:5]
	s_cbranch_vccnz .LBB0_85
	v_readlane_b32 s14, v100, 2
	s_nop 1
	v_mul_f32_e32 v59, s14, v59
.LBB0_85:
	ds_write_b32 v11, v59 offset:520
	s_and_b64 vcc, exec, s[0:1]
	v_cndmask_b32_e64 v59, 0, v71, s[4:5]
	s_cbranch_vccnz .LBB0_87
	v_readlane_b32 s14, v100, 3
	s_nop 1
	v_mul_f32_e32 v59, s14, v59
.LBB0_87:
	ds_write_b32 v11, v59 offset:780
	s_and_b64 vcc, exec, s[0:1]
	v_cndmask_b32_e64 v59, 0, v70, s[4:5]
	s_cbranch_vccnz .LBB0_89
	v_readlane_b32 s14, v100, 4
	s_nop 1
	v_mul_f32_e32 v59, s14, v59
.LBB0_89:
	ds_write_b32 v11, v59 offset:1040
	s_and_b64 vcc, exec, s[0:1]
	v_cndmask_b32_e64 v59, 0, v68, s[4:5]
	s_cbranch_vccnz .LBB0_91
	v_readlane_b32 s14, v100, 5
	s_nop 1
	v_mul_f32_e32 v59, s14, v59
.LBB0_91:
	ds_write_b32 v11, v59 offset:1300
	s_and_b64 vcc, exec, s[0:1]
	v_cndmask_b32_e64 v59, 0, v66, s[4:5]
	s_cbranch_vccnz .LBB0_93
	v_readlane_b32 s14, v100, 6
	s_nop 1
	v_mul_f32_e32 v59, s14, v59
.LBB0_93:
	ds_write_b32 v11, v59 offset:1560
	s_and_b64 vcc, exec, s[0:1]
	v_cndmask_b32_e64 v59, 0, v64, s[4:5]
	s_cbranch_vccnz .LBB0_95
	v_readlane_b32 s14, v100, 7
	s_nop 1
	v_mul_f32_e32 v59, s14, v59
.LBB0_95:
	ds_write_b32 v11, v59 offset:1820
	s_and_b64 vcc, exec, s[0:1]
	s_waitcnt vmcnt(55)
	v_cndmask_b32_e64 v59, 0, v69, s[4:5]
	s_cbranch_vccnz .LBB0_97
	v_readlane_b32 s14, v100, 8
	s_nop 1
	v_mul_f32_e32 v59, s14, v59
.LBB0_97:
	ds_write_b32 v11, v59 offset:2080
	s_and_b64 vcc, exec, s[0:1]
	s_waitcnt vmcnt(54)
	v_cndmask_b32_e64 v59, 0, v67, s[4:5]
	s_cbranch_vccnz .LBB0_99
	v_readlane_b32 s14, v100, 9
	s_nop 1
	v_mul_f32_e32 v59, s14, v59
.LBB0_99:
	ds_write_b32 v11, v59 offset:2340
	s_and_b64 vcc, exec, s[0:1]
	s_waitcnt vmcnt(53)
	v_cndmask_b32_e64 v59, 0, v65, s[4:5]
	s_cbranch_vccnz .LBB0_101
	v_readlane_b32 s14, v100, 10
	s_nop 1
	v_mul_f32_e32 v59, s14, v59
.LBB0_101:
	ds_write_b32 v11, v59 offset:2600
	s_and_b64 vcc, exec, s[0:1]
	s_waitcnt vmcnt(52)
	v_cndmask_b32_e64 v59, 0, v63, s[4:5]
	s_cbranch_vccnz .LBB0_103
	v_readlane_b32 s14, v100, 11
	s_nop 1
	v_mul_f32_e32 v59, s14, v59
.LBB0_103:
	ds_write_b32 v11, v59 offset:2860
	s_and_b64 vcc, exec, s[0:1]
	s_waitcnt vmcnt(51)
	v_cndmask_b32_e64 v59, 0, v62, s[4:5]
	s_cbranch_vccnz .LBB0_105
	v_readlane_b32 s14, v100, 12
	s_nop 1
	v_mul_f32_e32 v59, s14, v59
.LBB0_105:
	ds_write_b32 v11, v59 offset:3120
	s_and_b64 vcc, exec, s[0:1]
	s_waitcnt vmcnt(50)
	v_cndmask_b32_e64 v59, 0, v60, s[4:5]
	s_cbranch_vccnz .LBB0_107
	v_readlane_b32 s14, v100, 13
	s_nop 1
	v_mul_f32_e32 v59, s14, v59
.LBB0_107:
	s_and_b64 vcc, exec, s[0:1]
	s_waitcnt vmcnt(49)
	v_cndmask_b32_e64 v57, 0, v57, s[4:5]
	ds_write_b32 v11, v59 offset:3380
	s_cbranch_vccnz .LBB0_109
	v_readlane_b32 s14, v100, 14
	s_nop 1
	v_mul_f32_e32 v57, s14, v57
.LBB0_109:
	s_and_b64 vcc, exec, s[0:1]
	s_waitcnt vmcnt(48)
	v_cndmask_b32_e64 v55, 0, v55, s[4:5]
	ds_write_b32 v11, v57 offset:3640
	s_cbranch_vccnz .LBB0_111
	v_readlane_b32 s14, v100, 15
	s_nop 1
	v_mul_f32_e32 v55, s14, v55
.LBB0_111:
	ds_write_b32 v11, v55 offset:3900
	s_and_b64 vcc, exec, s[0:1]
	s_waitcnt vmcnt(47)
	v_cndmask_b32_e64 v55, 0, v61, s[4:5]
	s_cbranch_vccnz .LBB0_113
	v_readlane_b32 s14, v100, 16
	s_nop 1
	v_mul_f32_e32 v55, s14, v55
.LBB0_113:
	ds_write_b32 v11, v55 offset:4160
	s_and_b64 vcc, exec, s[0:1]
	s_waitcnt vmcnt(46)
	v_cndmask_b32_e64 v55, 0, v58, s[4:5]
	s_cbranch_vccnz .LBB0_115
	v_readlane_b32 s14, v100, 17
	s_nop 1
	v_mul_f32_e32 v55, s14, v55
.LBB0_115:
	ds_write_b32 v11, v55 offset:4420
	s_and_b64 vcc, exec, s[0:1]
	s_waitcnt vmcnt(45)
	v_cndmask_b32_e64 v55, 0, v56, s[4:5]
	s_cbranch_vccnz .LBB0_117
	v_readlane_b32 s14, v100, 18
	s_nop 1
	v_mul_f32_e32 v55, s14, v55
.LBB0_117:
	s_and_b64 vcc, exec, s[0:1]
	s_waitcnt vmcnt(44)
	v_cndmask_b32_e64 v54, 0, v54, s[4:5]
	ds_write_b32 v11, v55 offset:4680
	s_cbranch_vccnz .LBB0_119
	v_readlane_b32 s14, v100, 19
	s_nop 1
	v_mul_f32_e32 v54, s14, v54
.LBB0_119:
	s_and_b64 vcc, exec, s[0:1]
	s_waitcnt vmcnt(43)
	v_cndmask_b32_e64 v53, 0, v53, s[4:5]
	ds_write_b32 v11, v54 offset:4940
	s_cbranch_vccnz .LBB0_121
	v_readlane_b32 s14, v100, 20
	s_nop 1
	v_mul_f32_e32 v53, s14, v53
.LBB0_121:
	s_and_b64 vcc, exec, s[0:1]
	s_waitcnt vmcnt(42)
	v_cndmask_b32_e64 v51, 0, v51, s[4:5]
	ds_write_b32 v11, v53 offset:5200
	s_cbranch_vccnz .LBB0_123
	v_readlane_b32 s14, v100, 21
	s_nop 1
	v_mul_f32_e32 v51, s14, v51
.LBB0_123:
	s_and_b64 vcc, exec, s[0:1]
	s_waitcnt vmcnt(41)
	v_cndmask_b32_e64 v49, 0, v49, s[4:5]
	ds_write_b32 v11, v51 offset:5460
	s_cbranch_vccnz .LBB0_125
	v_readlane_b32 s14, v100, 22
	s_nop 1
	v_mul_f32_e32 v49, s14, v49
.LBB0_125:
	s_and_b64 vcc, exec, s[0:1]
	s_waitcnt vmcnt(40)
	v_cndmask_b32_e64 v47, 0, v47, s[4:5]
	ds_write_b32 v11, v49 offset:5720
	s_cbranch_vccnz .LBB0_127
	v_readlane_b32 s14, v100, 23
	s_nop 1
	v_mul_f32_e32 v47, s14, v47
.LBB0_127:
	ds_write_b32 v11, v47 offset:5980
	s_and_b64 vcc, exec, s[0:1]
	s_waitcnt vmcnt(39)
	v_cndmask_b32_e64 v47, 0, v52, s[4:5]
	s_cbranch_vccnz .LBB0_129
	v_readlane_b32 s14, v100, 24
	s_nop 1
	v_mul_f32_e32 v47, s14, v47
.LBB0_129:
	ds_write_b32 v11, v47 offset:6240
	s_and_b64 vcc, exec, s[0:1]
	s_waitcnt vmcnt(38)
	v_cndmask_b32_e64 v47, 0, v50, s[4:5]
	s_cbranch_vccnz .LBB0_131
	v_readlane_b32 s14, v100, 25
	s_nop 1
	v_mul_f32_e32 v47, s14, v47
.LBB0_131:
	ds_write_b32 v11, v47 offset:6500
	s_and_b64 vcc, exec, s[0:1]
	s_waitcnt vmcnt(37)
	v_cndmask_b32_e64 v47, 0, v48, s[4:5]
	s_cbranch_vccnz .LBB0_133
	v_readlane_b32 s14, v100, 26
	s_nop 1
	v_mul_f32_e32 v47, s14, v47
.LBB0_133:
	s_and_b64 vcc, exec, s[0:1]
	s_waitcnt vmcnt(36)
	v_cndmask_b32_e64 v46, 0, v46, s[4:5]
	ds_write_b32 v11, v47 offset:6760
	s_cbranch_vccnz .LBB0_135
	v_readlane_b32 s14, v100, 27
	s_nop 1
	v_mul_f32_e32 v46, s14, v46
.LBB0_135:
	s_and_b64 vcc, exec, s[0:1]
	s_waitcnt vmcnt(35)
	v_cndmask_b32_e64 v45, 0, v45, s[4:5]
	ds_write_b32 v11, v46 offset:7020
	s_cbranch_vccnz .LBB0_137
	v_readlane_b32 s14, v100, 28
	s_nop 1
	v_mul_f32_e32 v45, s14, v45
.LBB0_137:
	s_and_b64 vcc, exec, s[0:1]
	s_waitcnt vmcnt(34)
	v_cndmask_b32_e64 v43, 0, v43, s[4:5]
	ds_write_b32 v11, v45 offset:7280
	s_cbranch_vccnz .LBB0_139
	v_readlane_b32 s14, v100, 29
	s_nop 1
	v_mul_f32_e32 v43, s14, v43
.LBB0_139:
	s_and_b64 vcc, exec, s[0:1]
	s_waitcnt vmcnt(33)
	v_cndmask_b32_e64 v41, 0, v41, s[4:5]
	ds_write_b32 v11, v43 offset:7540
	s_cbranch_vccnz .LBB0_141
	v_readlane_b32 s14, v100, 30
	s_nop 1
	v_mul_f32_e32 v41, s14, v41
.LBB0_141:
	s_and_b64 vcc, exec, s[0:1]
	s_waitcnt vmcnt(32)
	v_cndmask_b32_e64 v39, 0, v39, s[4:5]
	ds_write_b32 v11, v41 offset:7800
	s_cbranch_vccnz .LBB0_143
	v_readlane_b32 s14, v100, 31
	s_nop 1
	v_mul_f32_e32 v39, s14, v39
.LBB0_143:
	ds_write_b32 v11, v39 offset:8060
	s_and_b64 vcc, exec, s[0:1]
	s_waitcnt vmcnt(31)
	v_cndmask_b32_e64 v39, 0, v44, s[4:5]
	s_cbranch_vccnz .LBB0_145
	v_readlane_b32 s14, v100, 32
	s_nop 1
	v_mul_f32_e32 v39, s14, v39
.LBB0_145:
	ds_write_b32 v11, v39 offset:8320
	s_and_b64 vcc, exec, s[0:1]
	s_waitcnt vmcnt(30)
	v_cndmask_b32_e64 v39, 0, v42, s[4:5]
	s_cbranch_vccnz .LBB0_147
	v_readlane_b32 s14, v100, 33
	s_nop 1
	v_mul_f32_e32 v39, s14, v39
.LBB0_147:
	ds_write_b32 v11, v39 offset:8580
	s_and_b64 vcc, exec, s[0:1]
	s_waitcnt vmcnt(29)
	v_cndmask_b32_e64 v39, 0, v40, s[4:5]
	s_cbranch_vccnz .LBB0_149
	v_readlane_b32 s14, v100, 34
	s_nop 1
	v_mul_f32_e32 v39, s14, v39
.LBB0_149:
	s_and_b64 vcc, exec, s[0:1]
	s_waitcnt vmcnt(28)
	v_cndmask_b32_e64 v38, 0, v38, s[4:5]
	ds_write_b32 v11, v39 offset:8840
	s_cbranch_vccnz .LBB0_151
	v_readlane_b32 s14, v100, 35
	s_nop 1
	v_mul_f32_e32 v38, s14, v38
.LBB0_151:
	s_and_b64 vcc, exec, s[0:1]
	s_waitcnt vmcnt(27)
	v_cndmask_b32_e64 v37, 0, v37, s[4:5]
	ds_write_b32 v11, v38 offset:9100
	s_cbranch_vccnz .LBB0_153
	v_readlane_b32 s14, v100, 36
	s_nop 1
	v_mul_f32_e32 v37, s14, v37
.LBB0_153:
	s_and_b64 vcc, exec, s[0:1]
	s_waitcnt vmcnt(26)
	v_cndmask_b32_e64 v35, 0, v35, s[4:5]
	ds_write_b32 v11, v37 offset:9360
	s_cbranch_vccnz .LBB0_155
	v_readlane_b32 s14, v100, 37
	s_nop 1
	v_mul_f32_e32 v35, s14, v35
.LBB0_155:
	s_and_b64 vcc, exec, s[0:1]
	s_waitcnt vmcnt(25)
	v_cndmask_b32_e64 v33, 0, v33, s[4:5]
	ds_write_b32 v11, v35 offset:9620
	s_cbranch_vccnz .LBB0_157
	v_readlane_b32 s14, v100, 38
	s_nop 1
	v_mul_f32_e32 v33, s14, v33
.LBB0_157:
	s_and_b64 vcc, exec, s[0:1]
	s_waitcnt vmcnt(24)
	v_cndmask_b32_e64 v31, 0, v31, s[4:5]
	ds_write_b32 v11, v33 offset:9880
	s_cbranch_vccnz .LBB0_159
	v_readlane_b32 s14, v100, 39
	s_nop 1
	v_mul_f32_e32 v31, s14, v31
.LBB0_159:
	ds_write_b32 v11, v31 offset:10140
	s_and_b64 vcc, exec, s[0:1]
	s_waitcnt vmcnt(23)
	v_cndmask_b32_e64 v31, 0, v36, s[4:5]
	s_cbranch_vccnz .LBB0_161
	v_readlane_b32 s14, v100, 40
	s_nop 1
	v_mul_f32_e32 v31, s14, v31
.LBB0_161:
	ds_write_b32 v11, v31 offset:10400
	s_and_b64 vcc, exec, s[0:1]
	s_waitcnt vmcnt(22)
	v_cndmask_b32_e64 v31, 0, v34, s[4:5]
	s_cbranch_vccnz .LBB0_163
	v_readlane_b32 s14, v100, 41
	s_nop 1
	v_mul_f32_e32 v31, s14, v31
.LBB0_163:
	ds_write_b32 v11, v31 offset:10660
	s_and_b64 vcc, exec, s[0:1]
	s_waitcnt vmcnt(21)
	v_cndmask_b32_e64 v31, 0, v32, s[4:5]
	s_cbranch_vccnz .LBB0_165
	v_readlane_b32 s14, v100, 42
	s_nop 1
	v_mul_f32_e32 v31, s14, v31
.LBB0_165:
	s_and_b64 vcc, exec, s[0:1]
	s_waitcnt vmcnt(20)
	v_cndmask_b32_e64 v30, 0, v30, s[4:5]
	ds_write_b32 v11, v31 offset:10920
	s_cbranch_vccnz .LBB0_167
	v_readlane_b32 s14, v100, 43
	s_nop 1
	v_mul_f32_e32 v30, s14, v30
.LBB0_167:
	s_and_b64 vcc, exec, s[0:1]
	s_waitcnt vmcnt(19)
	v_cndmask_b32_e64 v29, 0, v29, s[4:5]
	ds_write_b32 v11, v30 offset:11180
	s_cbranch_vccnz .LBB0_169
	v_readlane_b32 s14, v100, 44
	s_nop 1
	v_mul_f32_e32 v29, s14, v29
.LBB0_169:
	s_and_b64 vcc, exec, s[0:1]
	s_waitcnt vmcnt(18)
	v_cndmask_b32_e64 v27, 0, v27, s[4:5]
	ds_write_b32 v11, v29 offset:11440
	s_cbranch_vccnz .LBB0_171
	v_readlane_b32 s14, v100, 45
	s_nop 1
	v_mul_f32_e32 v27, s14, v27
.LBB0_171:
	s_and_b64 vcc, exec, s[0:1]
	s_waitcnt vmcnt(17)
	v_cndmask_b32_e64 v25, 0, v25, s[4:5]
	ds_write_b32 v11, v27 offset:11700
	s_cbranch_vccnz .LBB0_173
	v_readlane_b32 s14, v100, 46
	s_nop 1
	v_mul_f32_e32 v25, s14, v25
.LBB0_173:
	s_and_b64 vcc, exec, s[0:1]
	s_waitcnt vmcnt(16)
	v_cndmask_b32_e64 v23, 0, v23, s[4:5]
	ds_write_b32 v11, v25 offset:11960
	s_cbranch_vccnz .LBB0_175
	v_readlane_b32 s14, v100, 47
	s_nop 1
	v_mul_f32_e32 v23, s14, v23
.LBB0_175:
	ds_write_b32 v11, v23 offset:12220
	s_and_b64 vcc, exec, s[0:1]
	s_waitcnt vmcnt(15)
	v_cndmask_b32_e64 v23, 0, v28, s[4:5]
	s_cbranch_vccnz .LBB0_177
	v_readlane_b32 s14, v100, 48
	s_nop 1
	v_mul_f32_e32 v23, s14, v23
.LBB0_177:
	ds_write_b32 v11, v23 offset:12480
	s_and_b64 vcc, exec, s[0:1]
	s_waitcnt vmcnt(14)
	v_cndmask_b32_e64 v23, 0, v26, s[4:5]
	s_cbranch_vccnz .LBB0_179
	v_readlane_b32 s14, v100, 49
	s_nop 1
	v_mul_f32_e32 v23, s14, v23
.LBB0_179:
	ds_write_b32 v11, v23 offset:12740
	s_and_b64 vcc, exec, s[0:1]
	s_waitcnt vmcnt(13)
	v_cndmask_b32_e64 v23, 0, v24, s[4:5]
	s_cbranch_vccnz .LBB0_181
	v_readlane_b32 s14, v100, 50
	s_nop 1
	v_mul_f32_e32 v23, s14, v23
.LBB0_181:
	s_and_b64 vcc, exec, s[0:1]
	s_waitcnt vmcnt(12)
	v_cndmask_b32_e64 v22, 0, v22, s[4:5]
	ds_write_b32 v11, v23 offset:13000
	s_cbranch_vccnz .LBB0_183
	v_readlane_b32 s14, v100, 51
	s_nop 1
	v_mul_f32_e32 v22, s14, v22
.LBB0_183:
	s_and_b64 vcc, exec, s[0:1]
	s_waitcnt vmcnt(11)
	v_cndmask_b32_e64 v21, 0, v21, s[4:5]
	ds_write_b32 v11, v22 offset:13260
	s_cbranch_vccnz .LBB0_185
	v_readlane_b32 s14, v100, 52
	s_nop 1
	v_mul_f32_e32 v21, s14, v21
.LBB0_185:
	s_and_b64 vcc, exec, s[0:1]
	s_waitcnt vmcnt(10)
	v_cndmask_b32_e64 v19, 0, v19, s[4:5]
	ds_write_b32 v11, v21 offset:13520
	s_cbranch_vccnz .LBB0_187
	v_readlane_b32 s14, v100, 53
	s_nop 1
	v_mul_f32_e32 v19, s14, v19
.LBB0_187:
	s_and_b64 vcc, exec, s[0:1]
	s_waitcnt vmcnt(9)
	v_cndmask_b32_e64 v17, 0, v17, s[4:5]
	ds_write_b32 v11, v19 offset:13780
	s_cbranch_vccnz .LBB0_189
	v_readlane_b32 s14, v100, 54
	s_nop 1
	v_mul_f32_e32 v17, s14, v17
.LBB0_189:
	s_and_b64 vcc, exec, s[0:1]
	s_waitcnt vmcnt(8)
	v_cndmask_b32_e64 v15, 0, v15, s[4:5]
	ds_write_b32 v11, v17 offset:14040
	s_cbranch_vccnz .LBB0_191
	v_readlane_b32 s14, v100, 55
	s_nop 1
	v_mul_f32_e32 v15, s14, v15
.LBB0_191:
	ds_write_b32 v11, v15 offset:14300
	s_and_b64 vcc, exec, s[0:1]
	s_waitcnt vmcnt(7)
	v_cndmask_b32_e64 v15, 0, v20, s[4:5]
	s_cbranch_vccnz .LBB0_193
	v_readlane_b32 s14, v100, 56
	s_nop 1
	v_mul_f32_e32 v15, s14, v15
.LBB0_193:
	ds_write_b32 v11, v15 offset:14560
	s_and_b64 vcc, exec, s[0:1]
	s_waitcnt vmcnt(6)
	v_cndmask_b32_e64 v15, 0, v18, s[4:5]
	s_cbranch_vccnz .LBB0_195
	v_readlane_b32 s14, v100, 57
	s_nop 1
	v_mul_f32_e32 v15, s14, v15
.LBB0_195:
	ds_write_b32 v11, v15 offset:14820
	s_and_b64 vcc, exec, s[0:1]
	s_waitcnt vmcnt(5)
	v_cndmask_b32_e64 v15, 0, v16, s[4:5]
	s_cbranch_vccnz .LBB0_197
	v_readlane_b32 s14, v100, 58
	s_nop 1
	v_mul_f32_e32 v15, s14, v15
.LBB0_197:
	s_and_b64 vcc, exec, s[0:1]
	s_waitcnt vmcnt(4)
	v_cndmask_b32_e64 v9, 0, v9, s[4:5]
	ds_write_b32 v11, v15 offset:15080
	s_cbranch_vccnz .LBB0_199
	v_readlane_b32 s14, v100, 59
	s_nop 1
	v_mul_f32_e32 v9, s14, v9
.LBB0_199:
	s_and_b64 vcc, exec, s[0:1]
	s_waitcnt vmcnt(3)
	v_cndmask_b32_e64 v7, 0, v7, s[4:5]
	ds_write_b32 v11, v9 offset:15340
	s_cbranch_vccnz .LBB0_201
	v_readlane_b32 s14, v100, 60
	s_nop 1
	v_mul_f32_e32 v7, s14, v7
.LBB0_201:
	s_and_b64 vcc, exec, s[0:1]
	s_waitcnt vmcnt(2)
	v_cndmask_b32_e64 v6, 0, v6, s[4:5]
	ds_write_b32 v11, v7 offset:15600
	s_cbranch_vccnz .LBB0_203
	v_readlane_b32 s14, v100, 61
	s_nop 1
	v_mul_f32_e32 v6, s14, v6
.LBB0_203:
	s_and_b64 vcc, exec, s[0:1]
	s_waitcnt vmcnt(1)
	v_cndmask_b32_e64 v2, 0, v2, s[4:5]
	ds_write_b32 v11, v6 offset:15860
	s_cbranch_vccnz .LBB0_205
	v_readlane_b32 s14, v100, 62
	s_nop 1
	v_mul_f32_e32 v2, s14, v2
.LBB0_205:
	ds_write_b32 v11, v2 offset:16120
	s_and_b64 vcc, exec, s[0:1]
	s_waitcnt vmcnt(0)
	v_cndmask_b32_e64 v2, 0, v8, s[4:5]
	s_cbranch_vccnz .LBB0_59
	v_readlane_b32 s0, v100, 63
	s_nop 1
	v_mul_f32_e32 v2, s0, v2
	s_branch .LBB0_59
